# P1 narrow/meta GEMM: per-block operand loaded with fully coalesced instructions and staged through per-wave LDS tiles (on top of v96)
# speedup vs baseline: 1.0016x; 1.0016x over previous
.LBB0_237:
	s_waitcnt vmcnt(0)
	s_waitcnt vmcnt(0)
	v_and_b32_e32 v148, 63, v154
	v_lshrrev_b32_e32 v149, 6, v154
	v_and_b32_e32 v150, 31, v148
	v_lshrrev_b32_e32 v151, 5, v148
	v_lshlrev_b32_e32 v152, 6, v151
	v_lshl_or_b32 v152, v149, 9, v152
	s_add_u32 s50, s28, 0x4100000
	s_addc_u32 s51, s29, 0
	s_add_u32 s52, s28, 0x17400000
	s_addc_u32 s53, s29, 0
	s_add_u32 s54, s28, 0x7000000
	s_addc_u32 s55, s29, 0
	v_lshlrev_b32_e32 v153, 4, v148
	v_lshl_add_u32 v153, v149, 12, v153
	v_lshrrev_b32_e32 v157, 1, v149
	v_lshlrev_b32_e32 v156, 4, v148
	v_lshl_add_u32 v156, v157, 10, v156
	v_and_b32_e32 v159, 1, v149
	v_lshl_add_u32 v156, v159, 3, v156
	v_lshlrev_b32_e32 v158, 1, v159
	v_lshl_add_u32 v158, v157, 3, v158
	v_lshl_add_u32 v158, v151, 2, v158
	s_mov_b32 s58, 0
	s_sub_i32 s48, s2, 0xab
	s_cmp_lt_u32 s2, 0xab
	s_cselect_b32 s59, 1, 0
	s_movk_i32 s60, 0x55
	s_cselect_b32 s60, 0xab, s60
	s_movk_i32 s61, 0x100
	s_cselect_b32 s61, 0x201, s61
	s_cselect_b32 s48, s2, s48
	v_lshrrev_b32_e32 v190, 4, v148
	v_and_b32_e32 v191, 15, v148
	v_lshlrev_b32_e32 v191, 4, v191
	v_lshl_add_u32 v191, v149, 9, v191
	v_lshl_add_u32 v191, v190, 12, v191
	v_mul_u32_u24_e32 v188, 0x2200, v149
	v_add_u32_e32 v188, 0x10000, v188
	v_mul_u32_u24_e32 v189, 0x110, v150
	v_add_u32_e32 v189, v188, v189
	v_lshl_add_u32 v189, v151, 6, v189
	v_mul_u32_u24_e32 v190, 0x110, v190
	v_add_u32_e32 v188, v188, v190
	v_and_b32_e32 v190, 15, v148
	v_lshl_add_u32 v188, v190, 4, v188
	s_lshl_b32 s56, s60, 1
	s_add_i32 s56, s56, s60
	s_add_i32 s57, s48, s56
	s_movk_i32 s56, 0x4000
	s_cmp_eq_u32 s59, 1
	s_cselect_b32 s56, 0x2000, s56
	v_add_u32_e32 v146, s56, v150
	v_lshl_add_u32 v146, v146, 12, v152
	s_mov_b32 s46, s48
	s_cmp_eq_u32 s59, 1
	s_cbranch_scc0 .Lsl_meta
	global_load_dwordx4 v[64:67], v146, s[50:51]
	global_load_dwordx4 v[68:71], v146, s[50:51] offset:16
	global_load_dwordx4 v[72:75], v146, s[50:51] offset:32
	global_load_dwordx4 v[76:79], v146, s[50:51] offset:48
	global_load_dwordx4 v[80:83], v146, s[50:51] offset:128
	global_load_dwordx4 v[84:87], v146, s[50:51] offset:144
	global_load_dwordx4 v[88:91], v146, s[50:51] offset:160
	global_load_dwordx4 v[92:95], v146, s[50:51] offset:176
	global_load_dwordx4 v[96:99], v146, s[50:51] offset:256
	global_load_dwordx4 v[100:103], v146, s[50:51] offset:272
	global_load_dwordx4 v[104:107], v146, s[50:51] offset:288
	global_load_dwordx4 v[108:111], v146, s[50:51] offset:304
	global_load_dwordx4 v[112:115], v146, s[50:51] offset:384
	global_load_dwordx4 v[116:119], v146, s[50:51] offset:400
	global_load_dwordx4 v[120:123], v146, s[50:51] offset:416
	global_load_dwordx4 v[124:127], v146, s[50:51] offset:432
	s_lshl_b32 s56, s46, 17
	v_add_u32_e32 v180, s56, v191
	v_add_u32_e32 v181, 0x4000, v180
	v_add_u32_e32 v182, 0x8000, v180
	v_add_u32_e32 v183, 0xc000, v180
	v_add_u32_e32 v184, 0x10000, v180
	v_add_u32_e32 v185, 0x14000, v180
	v_add_u32_e32 v186, 0x18000, v180
	v_add_u32_e32 v187, 0x1c000, v180
	global_load_dwordx4 v[0:3], v180, s[28:29]
	global_load_dwordx4 v[4:7], v181, s[28:29]
	global_load_dwordx4 v[8:11], v182, s[28:29]
	global_load_dwordx4 v[12:15], v183, s[28:29]
	global_load_dwordx4 v[16:19], v184, s[28:29]
	global_load_dwordx4 v[20:23], v185, s[28:29]
	global_load_dwordx4 v[24:27], v186, s[28:29]
	global_load_dwordx4 v[28:31], v187, s[28:29]
	global_load_dwordx4 v[32:35], v180, s[28:29] offset:256
	global_load_dwordx4 v[36:39], v181, s[28:29] offset:256
	global_load_dwordx4 v[40:43], v182, s[28:29] offset:256
	global_load_dwordx4 v[44:47], v183, s[28:29] offset:256
	global_load_dwordx4 v[48:51], v184, s[28:29] offset:256
	global_load_dwordx4 v[52:55], v185, s[28:29] offset:256
	global_load_dwordx4 v[56:59], v186, s[28:29] offset:256
	global_load_dwordx4 v[60:63], v187, s[28:29] offset:256
	s_waitcnt vmcnt(8)
	ds_write_b128 v188, v[0:3]
	ds_write_b128 v188, v[4:7] offset:1088
	ds_write_b128 v188, v[8:11] offset:2176
	ds_write_b128 v188, v[12:15] offset:3264
	ds_write_b128 v188, v[16:19] offset:4352
	ds_write_b128 v188, v[20:23] offset:5440
	ds_write_b128 v188, v[24:27] offset:6528
	ds_write_b128 v188, v[28:31] offset:7616
	s_waitcnt lgkmcnt(4)
	ds_read_b128 v[192:195], v189
	ds_read_b128 v[196:199], v189 offset:16
	ds_read_b128 v[200:203], v189 offset:32
	ds_read_b128 v[204:207], v189 offset:48
	ds_read_b128 v[208:211], v189 offset:128
	ds_read_b128 v[212:215], v189 offset:144
	ds_read_b128 v[216:219], v189 offset:160
	ds_read_b128 v[220:223], v189 offset:176
	s_waitcnt lgkmcnt(7)
	v_mfma_f32_32x32x16_bf16 v[128:143], v[64:67], v[192:195], 0
	s_waitcnt lgkmcnt(6)
	v_mfma_f32_32x32x16_bf16 v[128:143], v[68:71], v[196:199], v[128:143]
	s_waitcnt lgkmcnt(5)
	v_mfma_f32_32x32x16_bf16 v[128:143], v[72:75], v[200:203], v[128:143]
	s_waitcnt lgkmcnt(4)
	v_mfma_f32_32x32x16_bf16 v[128:143], v[76:79], v[204:207], v[128:143]
	s_waitcnt lgkmcnt(3)
	v_mfma_f32_32x32x16_bf16 v[128:143], v[80:83], v[208:211], v[128:143]
	s_waitcnt lgkmcnt(2)
	v_mfma_f32_32x32x16_bf16 v[128:143], v[84:87], v[212:215], v[128:143]
	s_waitcnt lgkmcnt(1)
	v_mfma_f32_32x32x16_bf16 v[128:143], v[88:91], v[216:219], v[128:143]
	s_waitcnt lgkmcnt(0)
	v_mfma_f32_32x32x16_bf16 v[128:143], v[92:95], v[220:223], v[128:143]
	s_waitcnt vmcnt(0)
	ds_write_b128 v188, v[32:35]
	ds_write_b128 v188, v[36:39] offset:1088
	ds_write_b128 v188, v[40:43] offset:2176
	ds_write_b128 v188, v[44:47] offset:3264
	ds_write_b128 v188, v[48:51] offset:4352
	ds_write_b128 v188, v[52:55] offset:5440
	ds_write_b128 v188, v[56:59] offset:6528
	ds_write_b128 v188, v[60:63] offset:7616
	s_waitcnt lgkmcnt(4)
	ds_read_b128 v[192:195], v189
	ds_read_b128 v[196:199], v189 offset:16
	ds_read_b128 v[200:203], v189 offset:32
	ds_read_b128 v[204:207], v189 offset:48
	ds_read_b128 v[208:211], v189 offset:128
	ds_read_b128 v[212:215], v189 offset:144
	ds_read_b128 v[216:219], v189 offset:160
	ds_read_b128 v[220:223], v189 offset:176
	s_waitcnt lgkmcnt(7)
	v_mfma_f32_32x32x16_bf16 v[128:143], v[96:99], v[192:195], v[128:143]
	s_waitcnt lgkmcnt(6)
	v_mfma_f32_32x32x16_bf16 v[128:143], v[100:103], v[196:199], v[128:143]
	s_waitcnt lgkmcnt(5)
	v_mfma_f32_32x32x16_bf16 v[128:143], v[104:107], v[200:203], v[128:143]
	s_waitcnt lgkmcnt(4)
	v_mfma_f32_32x32x16_bf16 v[128:143], v[108:111], v[204:207], v[128:143]
	s_waitcnt lgkmcnt(3)
	v_mfma_f32_32x32x16_bf16 v[128:143], v[112:115], v[208:211], v[128:143]
	s_waitcnt lgkmcnt(2)
	v_mfma_f32_32x32x16_bf16 v[128:143], v[116:119], v[212:215], v[128:143]
	s_waitcnt lgkmcnt(1)
	v_mfma_f32_32x32x16_bf16 v[128:143], v[120:123], v[216:219], v[128:143]
	s_waitcnt lgkmcnt(0)
	v_mfma_f32_32x32x16_bf16 v[128:143], v[124:127], v[220:223], v[128:143]
	s_add_i32 s48, s46, s60
	s_lshl_b32 s56, s48, 17
	v_add_u32_e32 v180, s56, v191
	v_add_u32_e32 v181, 0x4000, v180
	v_add_u32_e32 v182, 0x8000, v180
	v_add_u32_e32 v183, 0xc000, v180
	v_add_u32_e32 v184, 0x10000, v180
	v_add_u32_e32 v185, 0x14000, v180
	v_add_u32_e32 v186, 0x18000, v180
	v_add_u32_e32 v187, 0x1c000, v180
	global_load_dwordx4 v[0:3], v180, s[28:29]
	global_load_dwordx4 v[4:7], v181, s[28:29]
	global_load_dwordx4 v[8:11], v182, s[28:29]
	global_load_dwordx4 v[12:15], v183, s[28:29]
	global_load_dwordx4 v[16:19], v184, s[28:29]
	global_load_dwordx4 v[20:23], v185, s[28:29]
	global_load_dwordx4 v[24:27], v186, s[28:29]
	global_load_dwordx4 v[28:31], v187, s[28:29]
	global_load_dwordx4 v[32:35], v180, s[28:29] offset:256
	global_load_dwordx4 v[36:39], v181, s[28:29] offset:256
	global_load_dwordx4 v[40:43], v182, s[28:29] offset:256
	global_load_dwordx4 v[44:47], v183, s[28:29] offset:256
	global_load_dwordx4 v[48:51], v184, s[28:29] offset:256
	global_load_dwordx4 v[52:55], v185, s[28:29] offset:256
	global_load_dwordx4 v[56:59], v186, s[28:29] offset:256
	global_load_dwordx4 v[60:63], v187, s[28:29] offset:256
	s_nop 15
	v_add_u32_e32 v160, s58, v153
	ds_write_b128 v160, v[128:131]
	ds_write_b128 v160, v[132:135] offset:1024
	ds_write_b128 v160, v[136:139] offset:2048
	ds_write_b128 v160, v[140:143] offset:3072
	s_waitcnt lgkmcnt(0)
	s_barrier
	v_add_u32_e32 v161, s58, v156
	ds_read_b64 v[162:163], v161
	ds_read_b64 v[164:165], v161 offset:4096
	ds_read_b64 v[166:167], v161 offset:8192
	ds_read_b64 v[168:169], v161 offset:12288
	ds_read_b64 v[170:171], v161 offset:16384
	ds_read_b64 v[172:173], v161 offset:20480
	ds_read_b64 v[174:175], v161 offset:24576
	ds_read_b64 v[176:177], v161 offset:28672
	s_xor_b32 s58, s58, 0x8000
	s_waitcnt lgkmcnt(0)
	v_add_f32_e32 v162, v162, v164
	v_add_f32_e32 v163, v163, v165
	v_add_f32_e32 v162, v162, v166
	v_add_f32_e32 v163, v163, v167
	v_add_f32_e32 v162, v162, v168
	v_add_f32_e32 v163, v163, v169
	v_add_f32_e32 v162, v162, v170
	v_add_f32_e32 v163, v163, v171
	v_add_f32_e32 v162, v162, v172
	v_add_f32_e32 v163, v163, v173
	v_add_f32_e32 v162, v162, v174
	v_add_f32_e32 v163, v163, v175
	v_add_f32_e32 v162, v162, v176
	v_add_f32_e32 v163, v163, v177
	s_lshl_b32 s56, s46, 5
	v_add_u32_e32 v164, s56, v150
	v_lshlrev_b32_e32 v164, 7, v164
	v_lshl_add_u32 v164, v158, 2, v164
	global_store_dwordx2 v164, v[162:163], s[52:53]
	s_mov_b32 s46, s48
	s_waitcnt vmcnt(8)
	ds_write_b128 v188, v[0:3]
	ds_write_b128 v188, v[4:7] offset:1088
	ds_write_b128 v188, v[8:11] offset:2176
	ds_write_b128 v188, v[12:15] offset:3264
	ds_write_b128 v188, v[16:19] offset:4352
	ds_write_b128 v188, v[20:23] offset:5440
	ds_write_b128 v188, v[24:27] offset:6528
	ds_write_b128 v188, v[28:31] offset:7616
	s_waitcnt lgkmcnt(4)
	ds_read_b128 v[192:195], v189
	ds_read_b128 v[196:199], v189 offset:16
	ds_read_b128 v[200:203], v189 offset:32
	ds_read_b128 v[204:207], v189 offset:48
	ds_read_b128 v[208:211], v189 offset:128
	ds_read_b128 v[212:215], v189 offset:144
	ds_read_b128 v[216:219], v189 offset:160
	ds_read_b128 v[220:223], v189 offset:176
	s_waitcnt lgkmcnt(7)
	v_mfma_f32_32x32x16_bf16 v[128:143], v[64:67], v[192:195], 0
	s_waitcnt lgkmcnt(6)
	v_mfma_f32_32x32x16_bf16 v[128:143], v[68:71], v[196:199], v[128:143]
	s_waitcnt lgkmcnt(5)
	v_mfma_f32_32x32x16_bf16 v[128:143], v[72:75], v[200:203], v[128:143]
	s_waitcnt lgkmcnt(4)
	v_mfma_f32_32x32x16_bf16 v[128:143], v[76:79], v[204:207], v[128:143]
	s_waitcnt lgkmcnt(3)
	v_mfma_f32_32x32x16_bf16 v[128:143], v[80:83], v[208:211], v[128:143]
	s_waitcnt lgkmcnt(2)
	v_mfma_f32_32x32x16_bf16 v[128:143], v[84:87], v[212:215], v[128:143]
	s_waitcnt lgkmcnt(1)
	v_mfma_f32_32x32x16_bf16 v[128:143], v[88:91], v[216:219], v[128:143]
	s_waitcnt lgkmcnt(0)
	v_mfma_f32_32x32x16_bf16 v[128:143], v[92:95], v[220:223], v[128:143]
	s_waitcnt vmcnt(1)
	ds_write_b128 v188, v[32:35]
	ds_write_b128 v188, v[36:39] offset:1088
	ds_write_b128 v188, v[40:43] offset:2176
	ds_write_b128 v188, v[44:47] offset:3264
	ds_write_b128 v188, v[48:51] offset:4352
	ds_write_b128 v188, v[52:55] offset:5440
	ds_write_b128 v188, v[56:59] offset:6528
	ds_write_b128 v188, v[60:63] offset:7616
	s_waitcnt lgkmcnt(4)
	ds_read_b128 v[192:195], v189
	ds_read_b128 v[196:199], v189 offset:16
	ds_read_b128 v[200:203], v189 offset:32
	ds_read_b128 v[204:207], v189 offset:48
	ds_read_b128 v[208:211], v189 offset:128
	ds_read_b128 v[212:215], v189 offset:144
	ds_read_b128 v[216:219], v189 offset:160
	ds_read_b128 v[220:223], v189 offset:176
	s_waitcnt lgkmcnt(7)
	v_mfma_f32_32x32x16_bf16 v[128:143], v[96:99], v[192:195], v[128:143]
	s_waitcnt lgkmcnt(6)
	v_mfma_f32_32x32x16_bf16 v[128:143], v[100:103], v[196:199], v[128:143]
	s_waitcnt lgkmcnt(5)
	v_mfma_f32_32x32x16_bf16 v[128:143], v[104:107], v[200:203], v[128:143]
	s_waitcnt lgkmcnt(4)
	v_mfma_f32_32x32x16_bf16 v[128:143], v[108:111], v[204:207], v[128:143]
	s_waitcnt lgkmcnt(3)
	v_mfma_f32_32x32x16_bf16 v[128:143], v[112:115], v[208:211], v[128:143]
	s_waitcnt lgkmcnt(2)
	v_mfma_f32_32x32x16_bf16 v[128:143], v[116:119], v[212:215], v[128:143]
	s_waitcnt lgkmcnt(1)
	v_mfma_f32_32x32x16_bf16 v[128:143], v[120:123], v[216:219], v[128:143]
	s_waitcnt lgkmcnt(0)
	v_mfma_f32_32x32x16_bf16 v[128:143], v[124:127], v[220:223], v[128:143]
	s_add_i32 s48, s46, s60
	s_lshl_b32 s56, s48, 17
	v_add_u32_e32 v180, s56, v191
	v_add_u32_e32 v181, 0x4000, v180
	v_add_u32_e32 v182, 0x8000, v180
	v_add_u32_e32 v183, 0xc000, v180
	v_add_u32_e32 v184, 0x10000, v180
	v_add_u32_e32 v185, 0x14000, v180
	v_add_u32_e32 v186, 0x18000, v180
	v_add_u32_e32 v187, 0x1c000, v180
	global_load_dwordx4 v[0:3], v180, s[28:29]
	global_load_dwordx4 v[4:7], v181, s[28:29]
	global_load_dwordx4 v[8:11], v182, s[28:29]
	global_load_dwordx4 v[12:15], v183, s[28:29]
	global_load_dwordx4 v[16:19], v184, s[28:29]
	global_load_dwordx4 v[20:23], v185, s[28:29]
	global_load_dwordx4 v[24:27], v186, s[28:29]
	global_load_dwordx4 v[28:31], v187, s[28:29]
	global_load_dwordx4 v[32:35], v180, s[28:29] offset:256
	global_load_dwordx4 v[36:39], v181, s[28:29] offset:256
	global_load_dwordx4 v[40:43], v182, s[28:29] offset:256
	global_load_dwordx4 v[44:47], v183, s[28:29] offset:256
	global_load_dwordx4 v[48:51], v184, s[28:29] offset:256
	global_load_dwordx4 v[52:55], v185, s[28:29] offset:256
	global_load_dwordx4 v[56:59], v186, s[28:29] offset:256
	global_load_dwordx4 v[60:63], v187, s[28:29] offset:256
	s_nop 15
	v_add_u32_e32 v160, s58, v153
	ds_write_b128 v160, v[128:131]
	ds_write_b128 v160, v[132:135] offset:1024
	ds_write_b128 v160, v[136:139] offset:2048
	ds_write_b128 v160, v[140:143] offset:3072
	s_waitcnt lgkmcnt(0)
	s_barrier
	v_add_u32_e32 v161, s58, v156
	ds_read_b64 v[162:163], v161
	ds_read_b64 v[164:165], v161 offset:4096
	ds_read_b64 v[166:167], v161 offset:8192
	ds_read_b64 v[168:169], v161 offset:12288
	ds_read_b64 v[170:171], v161 offset:16384
	ds_read_b64 v[172:173], v161 offset:20480
	ds_read_b64 v[174:175], v161 offset:24576
	ds_read_b64 v[176:177], v161 offset:28672
	s_xor_b32 s58, s58, 0x8000
	s_waitcnt lgkmcnt(0)
	v_add_f32_e32 v162, v162, v164
	v_add_f32_e32 v163, v163, v165
	v_add_f32_e32 v162, v162, v166
	v_add_f32_e32 v163, v163, v167
	v_add_f32_e32 v162, v162, v168
	v_add_f32_e32 v163, v163, v169
	v_add_f32_e32 v162, v162, v170
	v_add_f32_e32 v163, v163, v171
	v_add_f32_e32 v162, v162, v172
	v_add_f32_e32 v163, v163, v173
	v_add_f32_e32 v162, v162, v174
	v_add_f32_e32 v163, v163, v175
	v_add_f32_e32 v162, v162, v176
	v_add_f32_e32 v163, v163, v177
	s_lshl_b32 s56, s46, 5
	v_add_u32_e32 v164, s56, v150
	v_lshlrev_b32_e32 v164, 7, v164
	v_lshl_add_u32 v164, v158, 2, v164
	global_store_dwordx2 v164, v[162:163], s[52:53]
	s_mov_b32 s46, s48
	s_waitcnt vmcnt(8)
	ds_write_b128 v188, v[0:3]
	ds_write_b128 v188, v[4:7] offset:1088
	ds_write_b128 v188, v[8:11] offset:2176
	ds_write_b128 v188, v[12:15] offset:3264
	ds_write_b128 v188, v[16:19] offset:4352
	ds_write_b128 v188, v[20:23] offset:5440
	ds_write_b128 v188, v[24:27] offset:6528
	ds_write_b128 v188, v[28:31] offset:7616
	s_waitcnt lgkmcnt(4)
	ds_read_b128 v[192:195], v189
	ds_read_b128 v[196:199], v189 offset:16
	ds_read_b128 v[200:203], v189 offset:32
	ds_read_b128 v[204:207], v189 offset:48
	ds_read_b128 v[208:211], v189 offset:128
	ds_read_b128 v[212:215], v189 offset:144
	ds_read_b128 v[216:219], v189 offset:160
	ds_read_b128 v[220:223], v189 offset:176
	s_waitcnt lgkmcnt(7)
	v_mfma_f32_32x32x16_bf16 v[128:143], v[64:67], v[192:195], 0
	s_waitcnt lgkmcnt(6)
	v_mfma_f32_32x32x16_bf16 v[128:143], v[68:71], v[196:199], v[128:143]
	s_waitcnt lgkmcnt(5)
	v_mfma_f32_32x32x16_bf16 v[128:143], v[72:75], v[200:203], v[128:143]
	s_waitcnt lgkmcnt(4)
	v_mfma_f32_32x32x16_bf16 v[128:143], v[76:79], v[204:207], v[128:143]
	s_waitcnt lgkmcnt(3)
	v_mfma_f32_32x32x16_bf16 v[128:143], v[80:83], v[208:211], v[128:143]
	s_waitcnt lgkmcnt(2)
	v_mfma_f32_32x32x16_bf16 v[128:143], v[84:87], v[212:215], v[128:143]
	s_waitcnt lgkmcnt(1)
	v_mfma_f32_32x32x16_bf16 v[128:143], v[88:91], v[216:219], v[128:143]
	s_waitcnt lgkmcnt(0)
	v_mfma_f32_32x32x16_bf16 v[128:143], v[92:95], v[220:223], v[128:143]
	s_waitcnt vmcnt(1)
	ds_write_b128 v188, v[32:35]
	ds_write_b128 v188, v[36:39] offset:1088
	ds_write_b128 v188, v[40:43] offset:2176
	ds_write_b128 v188, v[44:47] offset:3264
	ds_write_b128 v188, v[48:51] offset:4352
	ds_write_b128 v188, v[52:55] offset:5440
	ds_write_b128 v188, v[56:59] offset:6528
	ds_write_b128 v188, v[60:63] offset:7616
	s_waitcnt lgkmcnt(4)
	ds_read_b128 v[192:195], v189
	ds_read_b128 v[196:199], v189 offset:16
	ds_read_b128 v[200:203], v189 offset:32
	ds_read_b128 v[204:207], v189 offset:48
	ds_read_b128 v[208:211], v189 offset:128
	ds_read_b128 v[212:215], v189 offset:144
	ds_read_b128 v[216:219], v189 offset:160
	ds_read_b128 v[220:223], v189 offset:176
	s_waitcnt lgkmcnt(7)
	v_mfma_f32_32x32x16_bf16 v[128:143], v[96:99], v[192:195], v[128:143]
	s_waitcnt lgkmcnt(6)
	v_mfma_f32_32x32x16_bf16 v[128:143], v[100:103], v[196:199], v[128:143]
	s_waitcnt lgkmcnt(5)
	v_mfma_f32_32x32x16_bf16 v[128:143], v[104:107], v[200:203], v[128:143]
	s_waitcnt lgkmcnt(4)
	v_mfma_f32_32x32x16_bf16 v[128:143], v[108:111], v[204:207], v[128:143]
	s_waitcnt lgkmcnt(3)
	v_mfma_f32_32x32x16_bf16 v[128:143], v[112:115], v[208:211], v[128:143]
	s_waitcnt lgkmcnt(2)
	v_mfma_f32_32x32x16_bf16 v[128:143], v[116:119], v[212:215], v[128:143]
	s_waitcnt lgkmcnt(1)
	v_mfma_f32_32x32x16_bf16 v[128:143], v[120:123], v[216:219], v[128:143]
	s_waitcnt lgkmcnt(0)
	v_mfma_f32_32x32x16_bf16 v[128:143], v[124:127], v[220:223], v[128:143]
	s_add_i32 s48, s46, s60
	s_cmp_lt_u32 s57, s61
	s_cbranch_scc0 .Lsl_no3_n
	s_lshl_b32 s56, s48, 17
	v_add_u32_e32 v180, s56, v191
	v_add_u32_e32 v181, 0x4000, v180
	v_add_u32_e32 v182, 0x8000, v180
	v_add_u32_e32 v183, 0xc000, v180
	v_add_u32_e32 v184, 0x10000, v180
	v_add_u32_e32 v185, 0x14000, v180
	v_add_u32_e32 v186, 0x18000, v180
	v_add_u32_e32 v187, 0x1c000, v180
	global_load_dwordx4 v[0:3], v180, s[28:29]
	global_load_dwordx4 v[4:7], v181, s[28:29]
	global_load_dwordx4 v[8:11], v182, s[28:29]
	global_load_dwordx4 v[12:15], v183, s[28:29]
	global_load_dwordx4 v[16:19], v184, s[28:29]
	global_load_dwordx4 v[20:23], v185, s[28:29]
	global_load_dwordx4 v[24:27], v186, s[28:29]
	global_load_dwordx4 v[28:31], v187, s[28:29]
	global_load_dwordx4 v[32:35], v180, s[28:29] offset:256
	global_load_dwordx4 v[36:39], v181, s[28:29] offset:256
	global_load_dwordx4 v[40:43], v182, s[28:29] offset:256
	global_load_dwordx4 v[44:47], v183, s[28:29] offset:256
	global_load_dwordx4 v[48:51], v184, s[28:29] offset:256
	global_load_dwordx4 v[52:55], v185, s[28:29] offset:256
	global_load_dwordx4 v[56:59], v186, s[28:29] offset:256
	global_load_dwordx4 v[60:63], v187, s[28:29] offset:256
.Lsl_no3_n:
	s_nop 15
	v_add_u32_e32 v160, s58, v153
	ds_write_b128 v160, v[128:131]
	ds_write_b128 v160, v[132:135] offset:1024
	ds_write_b128 v160, v[136:139] offset:2048
	ds_write_b128 v160, v[140:143] offset:3072
	s_waitcnt lgkmcnt(0)
	s_barrier
	v_add_u32_e32 v161, s58, v156
	ds_read_b64 v[162:163], v161
	ds_read_b64 v[164:165], v161 offset:4096
	ds_read_b64 v[166:167], v161 offset:8192
	ds_read_b64 v[168:169], v161 offset:12288
	ds_read_b64 v[170:171], v161 offset:16384
	ds_read_b64 v[172:173], v161 offset:20480
	ds_read_b64 v[174:175], v161 offset:24576
	ds_read_b64 v[176:177], v161 offset:28672
	s_xor_b32 s58, s58, 0x8000
	s_waitcnt lgkmcnt(0)
	v_add_f32_e32 v162, v162, v164
	v_add_f32_e32 v163, v163, v165
	v_add_f32_e32 v162, v162, v166
	v_add_f32_e32 v163, v163, v167
	v_add_f32_e32 v162, v162, v168
	v_add_f32_e32 v163, v163, v169
	v_add_f32_e32 v162, v162, v170
	v_add_f32_e32 v163, v163, v171
	v_add_f32_e32 v162, v162, v172
	v_add_f32_e32 v163, v163, v173
	v_add_f32_e32 v162, v162, v174
	v_add_f32_e32 v163, v163, v175
	v_add_f32_e32 v162, v162, v176
	v_add_f32_e32 v163, v163, v177
	s_lshl_b32 s56, s46, 5
	v_add_u32_e32 v164, s56, v150
	v_lshlrev_b32_e32 v164, 7, v164
	v_lshl_add_u32 v164, v158, 2, v164
	global_store_dwordx2 v164, v[162:163], s[52:53]
	s_mov_b32 s46, s48
	s_cmp_lt_u32 s57, s61
	s_cbranch_scc0 .Lsl_done
	s_waitcnt vmcnt(8)
	ds_write_b128 v188, v[0:3]
	ds_write_b128 v188, v[4:7] offset:1088
	ds_write_b128 v188, v[8:11] offset:2176
	ds_write_b128 v188, v[12:15] offset:3264
	ds_write_b128 v188, v[16:19] offset:4352
	ds_write_b128 v188, v[20:23] offset:5440
	ds_write_b128 v188, v[24:27] offset:6528
	ds_write_b128 v188, v[28:31] offset:7616
	s_waitcnt lgkmcnt(4)
	ds_read_b128 v[192:195], v189
	ds_read_b128 v[196:199], v189 offset:16
	ds_read_b128 v[200:203], v189 offset:32
	ds_read_b128 v[204:207], v189 offset:48
	ds_read_b128 v[208:211], v189 offset:128
	ds_read_b128 v[212:215], v189 offset:144
	ds_read_b128 v[216:219], v189 offset:160
	ds_read_b128 v[220:223], v189 offset:176
	s_waitcnt lgkmcnt(7)
	v_mfma_f32_32x32x16_bf16 v[128:143], v[64:67], v[192:195], 0
	s_waitcnt lgkmcnt(6)
	v_mfma_f32_32x32x16_bf16 v[128:143], v[68:71], v[196:199], v[128:143]
	s_waitcnt lgkmcnt(5)
	v_mfma_f32_32x32x16_bf16 v[128:143], v[72:75], v[200:203], v[128:143]
	s_waitcnt lgkmcnt(4)
	v_mfma_f32_32x32x16_bf16 v[128:143], v[76:79], v[204:207], v[128:143]
	s_waitcnt lgkmcnt(3)
	v_mfma_f32_32x32x16_bf16 v[128:143], v[80:83], v[208:211], v[128:143]
	s_waitcnt lgkmcnt(2)
	v_mfma_f32_32x32x16_bf16 v[128:143], v[84:87], v[212:215], v[128:143]
	s_waitcnt lgkmcnt(1)
	v_mfma_f32_32x32x16_bf16 v[128:143], v[88:91], v[216:219], v[128:143]
	s_waitcnt lgkmcnt(0)
	v_mfma_f32_32x32x16_bf16 v[128:143], v[92:95], v[220:223], v[128:143]
	s_waitcnt vmcnt(1)
	ds_write_b128 v188, v[32:35]
	ds_write_b128 v188, v[36:39] offset:1088
	ds_write_b128 v188, v[40:43] offset:2176
	ds_write_b128 v188, v[44:47] offset:3264
	ds_write_b128 v188, v[48:51] offset:4352
	ds_write_b128 v188, v[52:55] offset:5440
	ds_write_b128 v188, v[56:59] offset:6528
	ds_write_b128 v188, v[60:63] offset:7616
	s_waitcnt lgkmcnt(4)
	ds_read_b128 v[192:195], v189
	ds_read_b128 v[196:199], v189 offset:16
	ds_read_b128 v[200:203], v189 offset:32
	ds_read_b128 v[204:207], v189 offset:48
	ds_read_b128 v[208:211], v189 offset:128
	ds_read_b128 v[212:215], v189 offset:144
	ds_read_b128 v[216:219], v189 offset:160
	ds_read_b128 v[220:223], v189 offset:176
	s_waitcnt lgkmcnt(7)
	v_mfma_f32_32x32x16_bf16 v[128:143], v[96:99], v[192:195], v[128:143]
	s_waitcnt lgkmcnt(6)
	v_mfma_f32_32x32x16_bf16 v[128:143], v[100:103], v[196:199], v[128:143]
	s_waitcnt lgkmcnt(5)
	v_mfma_f32_32x32x16_bf16 v[128:143], v[104:107], v[200:203], v[128:143]
	s_waitcnt lgkmcnt(4)
	v_mfma_f32_32x32x16_bf16 v[128:143], v[108:111], v[204:207], v[128:143]
	s_waitcnt lgkmcnt(3)
	v_mfma_f32_32x32x16_bf16 v[128:143], v[112:115], v[208:211], v[128:143]
	s_waitcnt lgkmcnt(2)
	v_mfma_f32_32x32x16_bf16 v[128:143], v[116:119], v[212:215], v[128:143]
	s_waitcnt lgkmcnt(1)
	v_mfma_f32_32x32x16_bf16 v[128:143], v[120:123], v[216:219], v[128:143]
	s_waitcnt lgkmcnt(0)
	v_mfma_f32_32x32x16_bf16 v[128:143], v[124:127], v[220:223], v[128:143]
	s_nop 15
	v_add_u32_e32 v160, s58, v153
	ds_write_b128 v160, v[128:131]
	ds_write_b128 v160, v[132:135] offset:1024
	ds_write_b128 v160, v[136:139] offset:2048
	ds_write_b128 v160, v[140:143] offset:3072
	s_waitcnt lgkmcnt(0)
	s_barrier
	v_add_u32_e32 v161, s58, v156
	ds_read_b64 v[162:163], v161
	ds_read_b64 v[164:165], v161 offset:4096
	ds_read_b64 v[166:167], v161 offset:8192
	ds_read_b64 v[168:169], v161 offset:12288
	ds_read_b64 v[170:171], v161 offset:16384
	ds_read_b64 v[172:173], v161 offset:20480
	ds_read_b64 v[174:175], v161 offset:24576
	ds_read_b64 v[176:177], v161 offset:28672
	s_xor_b32 s58, s58, 0x8000
	s_waitcnt lgkmcnt(0)
	v_add_f32_e32 v162, v162, v164
	v_add_f32_e32 v163, v163, v165
	v_add_f32_e32 v162, v162, v166
	v_add_f32_e32 v163, v163, v167
	v_add_f32_e32 v162, v162, v168
	v_add_f32_e32 v163, v163, v169
	v_add_f32_e32 v162, v162, v170
	v_add_f32_e32 v163, v163, v171
	v_add_f32_e32 v162, v162, v172
	v_add_f32_e32 v163, v163, v173
	v_add_f32_e32 v162, v162, v174
	v_add_f32_e32 v163, v163, v175
	v_add_f32_e32 v162, v162, v176
	v_add_f32_e32 v163, v163, v177
	s_lshl_b32 s56, s46, 5
	v_add_u32_e32 v164, s56, v150
	v_lshlrev_b32_e32 v164, 7, v164
	v_lshl_add_u32 v164, v158, 2, v164
	global_store_dwordx2 v164, v[162:163], s[52:53]
	s_branch .Lsl_done
.Lsl_meta:
	global_load_dwordx4 v[64:67], v146, s[28:29]
	global_load_dwordx4 v[68:71], v146, s[28:29] offset:16
	global_load_dwordx4 v[72:75], v146, s[28:29] offset:32
	global_load_dwordx4 v[76:79], v146, s[28:29] offset:48
	global_load_dwordx4 v[80:83], v146, s[28:29] offset:128
	global_load_dwordx4 v[84:87], v146, s[28:29] offset:144
	global_load_dwordx4 v[88:91], v146, s[28:29] offset:160
	global_load_dwordx4 v[92:95], v146, s[28:29] offset:176
	global_load_dwordx4 v[96:99], v146, s[28:29] offset:256
	global_load_dwordx4 v[100:103], v146, s[28:29] offset:272
	global_load_dwordx4 v[104:107], v146, s[28:29] offset:288
	global_load_dwordx4 v[108:111], v146, s[28:29] offset:304
	global_load_dwordx4 v[112:115], v146, s[28:29] offset:384
	global_load_dwordx4 v[116:119], v146, s[28:29] offset:400
	global_load_dwordx4 v[120:123], v146, s[28:29] offset:416
	global_load_dwordx4 v[124:127], v146, s[28:29] offset:432
	s_lshl_b32 s56, s46, 17
	v_add_u32_e32 v180, s56, v191
	v_add_u32_e32 v181, 0x4000, v180
	v_add_u32_e32 v182, 0x8000, v180
	v_add_u32_e32 v183, 0xc000, v180
	v_add_u32_e32 v184, 0x10000, v180
	v_add_u32_e32 v185, 0x14000, v180
	v_add_u32_e32 v186, 0x18000, v180
	v_add_u32_e32 v187, 0x1c000, v180
	global_load_dwordx4 v[0:3], v180, s[50:51]
	global_load_dwordx4 v[4:7], v181, s[50:51]
	global_load_dwordx4 v[8:11], v182, s[50:51]
	global_load_dwordx4 v[12:15], v183, s[50:51]
	global_load_dwordx4 v[16:19], v184, s[50:51]
	global_load_dwordx4 v[20:23], v185, s[50:51]
	global_load_dwordx4 v[24:27], v186, s[50:51]
	global_load_dwordx4 v[28:31], v187, s[50:51]
	global_load_dwordx4 v[32:35], v180, s[50:51] offset:256
	global_load_dwordx4 v[36:39], v181, s[50:51] offset:256
	global_load_dwordx4 v[40:43], v182, s[50:51] offset:256
	global_load_dwordx4 v[44:47], v183, s[50:51] offset:256
	global_load_dwordx4 v[48:51], v184, s[50:51] offset:256
	global_load_dwordx4 v[52:55], v185, s[50:51] offset:256
	global_load_dwordx4 v[56:59], v186, s[50:51] offset:256
	global_load_dwordx4 v[60:63], v187, s[50:51] offset:256
	s_waitcnt vmcnt(8)
	ds_write_b128 v188, v[0:3]
	ds_write_b128 v188, v[4:7] offset:1088
	ds_write_b128 v188, v[8:11] offset:2176
	ds_write_b128 v188, v[12:15] offset:3264
	ds_write_b128 v188, v[16:19] offset:4352
	ds_write_b128 v188, v[20:23] offset:5440
	ds_write_b128 v188, v[24:27] offset:6528
	ds_write_b128 v188, v[28:31] offset:7616
	s_waitcnt lgkmcnt(4)
	ds_read_b128 v[192:195], v189
	ds_read_b128 v[196:199], v189 offset:16
	ds_read_b128 v[200:203], v189 offset:32
	ds_read_b128 v[204:207], v189 offset:48
	ds_read_b128 v[208:211], v189 offset:128
	ds_read_b128 v[212:215], v189 offset:144
	ds_read_b128 v[216:219], v189 offset:160
	ds_read_b128 v[220:223], v189 offset:176
	s_waitcnt lgkmcnt(7)
	v_mfma_f32_32x32x16_bf16 v[128:143], v[192:195], v[64:67], 0
	s_waitcnt lgkmcnt(6)
	v_mfma_f32_32x32x16_bf16 v[128:143], v[196:199], v[68:71], v[128:143]
	s_waitcnt lgkmcnt(5)
	v_mfma_f32_32x32x16_bf16 v[128:143], v[200:203], v[72:75], v[128:143]
	s_waitcnt lgkmcnt(4)
	v_mfma_f32_32x32x16_bf16 v[128:143], v[204:207], v[76:79], v[128:143]
	s_waitcnt lgkmcnt(3)
	v_mfma_f32_32x32x16_bf16 v[128:143], v[208:211], v[80:83], v[128:143]
	s_waitcnt lgkmcnt(2)
	v_mfma_f32_32x32x16_bf16 v[128:143], v[212:215], v[84:87], v[128:143]
	s_waitcnt lgkmcnt(1)
	v_mfma_f32_32x32x16_bf16 v[128:143], v[216:219], v[88:91], v[128:143]
	s_waitcnt lgkmcnt(0)
	v_mfma_f32_32x32x16_bf16 v[128:143], v[220:223], v[92:95], v[128:143]
	s_waitcnt vmcnt(0)
	ds_write_b128 v188, v[32:35]
	ds_write_b128 v188, v[36:39] offset:1088
	ds_write_b128 v188, v[40:43] offset:2176
	ds_write_b128 v188, v[44:47] offset:3264
	ds_write_b128 v188, v[48:51] offset:4352
	ds_write_b128 v188, v[52:55] offset:5440
	ds_write_b128 v188, v[56:59] offset:6528
	ds_write_b128 v188, v[60:63] offset:7616
	s_waitcnt lgkmcnt(4)
	ds_read_b128 v[192:195], v189
	ds_read_b128 v[196:199], v189 offset:16
	ds_read_b128 v[200:203], v189 offset:32
	ds_read_b128 v[204:207], v189 offset:48
	ds_read_b128 v[208:211], v189 offset:128
	ds_read_b128 v[212:215], v189 offset:144
	ds_read_b128 v[216:219], v189 offset:160
	ds_read_b128 v[220:223], v189 offset:176
	s_waitcnt lgkmcnt(7)
	v_mfma_f32_32x32x16_bf16 v[128:143], v[192:195], v[96:99], v[128:143]
	s_waitcnt lgkmcnt(6)
	v_mfma_f32_32x32x16_bf16 v[128:143], v[196:199], v[100:103], v[128:143]
	s_waitcnt lgkmcnt(5)
	v_mfma_f32_32x32x16_bf16 v[128:143], v[200:203], v[104:107], v[128:143]
	s_waitcnt lgkmcnt(4)
	v_mfma_f32_32x32x16_bf16 v[128:143], v[204:207], v[108:111], v[128:143]
	s_waitcnt lgkmcnt(3)
	v_mfma_f32_32x32x16_bf16 v[128:143], v[208:211], v[112:115], v[128:143]
	s_waitcnt lgkmcnt(2)
	v_mfma_f32_32x32x16_bf16 v[128:143], v[212:215], v[116:119], v[128:143]
	s_waitcnt lgkmcnt(1)
	v_mfma_f32_32x32x16_bf16 v[128:143], v[216:219], v[120:123], v[128:143]
	s_waitcnt lgkmcnt(0)
	v_mfma_f32_32x32x16_bf16 v[128:143], v[220:223], v[124:127], v[128:143]
	s_add_i32 s48, s46, s60
	s_lshl_b32 s56, s48, 17
	v_add_u32_e32 v180, s56, v191
	v_add_u32_e32 v181, 0x4000, v180
	v_add_u32_e32 v182, 0x8000, v180
	v_add_u32_e32 v183, 0xc000, v180
	v_add_u32_e32 v184, 0x10000, v180
	v_add_u32_e32 v185, 0x14000, v180
	v_add_u32_e32 v186, 0x18000, v180
	v_add_u32_e32 v187, 0x1c000, v180
	global_load_dwordx4 v[0:3], v180, s[50:51]
	global_load_dwordx4 v[4:7], v181, s[50:51]
	global_load_dwordx4 v[8:11], v182, s[50:51]
	global_load_dwordx4 v[12:15], v183, s[50:51]
	global_load_dwordx4 v[16:19], v184, s[50:51]
	global_load_dwordx4 v[20:23], v185, s[50:51]
	global_load_dwordx4 v[24:27], v186, s[50:51]
	global_load_dwordx4 v[28:31], v187, s[50:51]
	global_load_dwordx4 v[32:35], v180, s[50:51] offset:256
	global_load_dwordx4 v[36:39], v181, s[50:51] offset:256
	global_load_dwordx4 v[40:43], v182, s[50:51] offset:256
	global_load_dwordx4 v[44:47], v183, s[50:51] offset:256
	global_load_dwordx4 v[48:51], v184, s[50:51] offset:256
	global_load_dwordx4 v[52:55], v185, s[50:51] offset:256
	global_load_dwordx4 v[56:59], v186, s[50:51] offset:256
	global_load_dwordx4 v[60:63], v187, s[50:51] offset:256
	s_nop 15
	v_add_u32_e32 v160, s58, v153
	ds_write_b128 v160, v[128:131]
	ds_write_b128 v160, v[132:135] offset:1024
	ds_write_b128 v160, v[136:139] offset:2048
	ds_write_b128 v160, v[140:143] offset:3072
	s_waitcnt lgkmcnt(0)
	s_barrier
	v_add_u32_e32 v161, s58, v156
	ds_read_b64 v[162:163], v161
	ds_read_b64 v[164:165], v161 offset:4096
	ds_read_b64 v[166:167], v161 offset:8192
	ds_read_b64 v[168:169], v161 offset:12288
	ds_read_b64 v[170:171], v161 offset:16384
	ds_read_b64 v[172:173], v161 offset:20480
	ds_read_b64 v[174:175], v161 offset:24576
	ds_read_b64 v[176:177], v161 offset:28672
	s_xor_b32 s58, s58, 0x8000
	s_waitcnt lgkmcnt(0)
	v_add_f32_e32 v162, v162, v164
	v_add_f32_e32 v163, v163, v165
	v_add_f32_e32 v162, v162, v166
	v_add_f32_e32 v163, v163, v167
	v_add_f32_e32 v162, v162, v168
	v_add_f32_e32 v163, v163, v169
	v_add_f32_e32 v162, v162, v170
	v_add_f32_e32 v163, v163, v171
	v_add_f32_e32 v162, v162, v172
	v_add_f32_e32 v163, v163, v173
	v_add_f32_e32 v162, v162, v174
	v_add_f32_e32 v163, v163, v175
	v_add_f32_e32 v162, v162, v176
	v_add_f32_e32 v163, v163, v177
	s_lshr_b32 s56, s46, 3
	s_and_b32 s56, s56, 12
	s_cmp_eq_u32 s56, 12
	s_cbranch_scc0 .Lsl_nogate_m0
	v_mul_f32_e32 v164, 0xbfb8aa3b, v162
	v_mul_f32_e32 v165, 0xbfb8aa3b, v163
	v_exp_f32_e32 v164, v164
	v_exp_f32_e32 v165, v165
	s_nop 0
	v_add_f32_e32 v164, 1.0, v164
	v_add_f32_e32 v165, 1.0, v165
	v_rcp_f32_e32 v164, v164
	v_rcp_f32_e32 v165, v165
	s_nop 0
	v_mul_f32_e32 v162, v162, v164
	v_mul_f32_e32 v163, v163, v165
.Lsl_nogate_m0:
	v_cvt_pk_bf16_f32 v162, v162, v163
	v_add_u32_e32 v164, 0x4000, v150
	v_lshlrev_b32_e32 v164, 14, v164
	s_lshl_b32 s56, s46, 6
	v_lshl_add_u32 v165, v158, 1, s56
	v_add_u32_e32 v164, v164, v165
	global_store_dword v164, v162, s[54:55]
	s_mov_b32 s46, s48
	s_waitcnt vmcnt(8)
	ds_write_b128 v188, v[0:3]
	ds_write_b128 v188, v[4:7] offset:1088
	ds_write_b128 v188, v[8:11] offset:2176
	ds_write_b128 v188, v[12:15] offset:3264
	ds_write_b128 v188, v[16:19] offset:4352
	ds_write_b128 v188, v[20:23] offset:5440
	ds_write_b128 v188, v[24:27] offset:6528
	ds_write_b128 v188, v[28:31] offset:7616
	s_waitcnt lgkmcnt(4)
	ds_read_b128 v[192:195], v189
	ds_read_b128 v[196:199], v189 offset:16
	ds_read_b128 v[200:203], v189 offset:32
	ds_read_b128 v[204:207], v189 offset:48
	ds_read_b128 v[208:211], v189 offset:128
	ds_read_b128 v[212:215], v189 offset:144
	ds_read_b128 v[216:219], v189 offset:160
	ds_read_b128 v[220:223], v189 offset:176
	s_waitcnt lgkmcnt(7)
	v_mfma_f32_32x32x16_bf16 v[128:143], v[192:195], v[64:67], 0
	s_waitcnt lgkmcnt(6)
	v_mfma_f32_32x32x16_bf16 v[128:143], v[196:199], v[68:71], v[128:143]
	s_waitcnt lgkmcnt(5)
	v_mfma_f32_32x32x16_bf16 v[128:143], v[200:203], v[72:75], v[128:143]
	s_waitcnt lgkmcnt(4)
	v_mfma_f32_32x32x16_bf16 v[128:143], v[204:207], v[76:79], v[128:143]
	s_waitcnt lgkmcnt(3)
	v_mfma_f32_32x32x16_bf16 v[128:143], v[208:211], v[80:83], v[128:143]
	s_waitcnt lgkmcnt(2)
	v_mfma_f32_32x32x16_bf16 v[128:143], v[212:215], v[84:87], v[128:143]
	s_waitcnt lgkmcnt(1)
	v_mfma_f32_32x32x16_bf16 v[128:143], v[216:219], v[88:91], v[128:143]
	s_waitcnt lgkmcnt(0)
	v_mfma_f32_32x32x16_bf16 v[128:143], v[220:223], v[92:95], v[128:143]
	s_waitcnt vmcnt(1)
	ds_write_b128 v188, v[32:35]
	ds_write_b128 v188, v[36:39] offset:1088
	ds_write_b128 v188, v[40:43] offset:2176
	ds_write_b128 v188, v[44:47] offset:3264
	ds_write_b128 v188, v[48:51] offset:4352
	ds_write_b128 v188, v[52:55] offset:5440
	ds_write_b128 v188, v[56:59] offset:6528
	ds_write_b128 v188, v[60:63] offset:7616
	s_waitcnt lgkmcnt(4)
	ds_read_b128 v[192:195], v189
	ds_read_b128 v[196:199], v189 offset:16
	ds_read_b128 v[200:203], v189 offset:32
	ds_read_b128 v[204:207], v189 offset:48
	ds_read_b128 v[208:211], v189 offset:128
	ds_read_b128 v[212:215], v189 offset:144
	ds_read_b128 v[216:219], v189 offset:160
	ds_read_b128 v[220:223], v189 offset:176
	s_waitcnt lgkmcnt(7)
	v_mfma_f32_32x32x16_bf16 v[128:143], v[192:195], v[96:99], v[128:143]
	s_waitcnt lgkmcnt(6)
	v_mfma_f32_32x32x16_bf16 v[128:143], v[196:199], v[100:103], v[128:143]
	s_waitcnt lgkmcnt(5)
	v_mfma_f32_32x32x16_bf16 v[128:143], v[200:203], v[104:107], v[128:143]
	s_waitcnt lgkmcnt(4)
	v_mfma_f32_32x32x16_bf16 v[128:143], v[204:207], v[108:111], v[128:143]
	s_waitcnt lgkmcnt(3)
	v_mfma_f32_32x32x16_bf16 v[128:143], v[208:211], v[112:115], v[128:143]
	s_waitcnt lgkmcnt(2)
	v_mfma_f32_32x32x16_bf16 v[128:143], v[212:215], v[116:119], v[128:143]
	s_waitcnt lgkmcnt(1)
	v_mfma_f32_32x32x16_bf16 v[128:143], v[216:219], v[120:123], v[128:143]
	s_waitcnt lgkmcnt(0)
	v_mfma_f32_32x32x16_bf16 v[128:143], v[220:223], v[124:127], v[128:143]
	s_add_i32 s48, s46, s60
	s_lshl_b32 s56, s48, 17
	v_add_u32_e32 v180, s56, v191
	v_add_u32_e32 v181, 0x4000, v180
	v_add_u32_e32 v182, 0x8000, v180
	v_add_u32_e32 v183, 0xc000, v180
	v_add_u32_e32 v184, 0x10000, v180
	v_add_u32_e32 v185, 0x14000, v180
	v_add_u32_e32 v186, 0x18000, v180
	v_add_u32_e32 v187, 0x1c000, v180
	global_load_dwordx4 v[0:3], v180, s[50:51]
	global_load_dwordx4 v[4:7], v181, s[50:51]
	global_load_dwordx4 v[8:11], v182, s[50:51]
	global_load_dwordx4 v[12:15], v183, s[50:51]
	global_load_dwordx4 v[16:19], v184, s[50:51]
	global_load_dwordx4 v[20:23], v185, s[50:51]
	global_load_dwordx4 v[24:27], v186, s[50:51]
	global_load_dwordx4 v[28:31], v187, s[50:51]
	global_load_dwordx4 v[32:35], v180, s[50:51] offset:256
	global_load_dwordx4 v[36:39], v181, s[50:51] offset:256
	global_load_dwordx4 v[40:43], v182, s[50:51] offset:256
	global_load_dwordx4 v[44:47], v183, s[50:51] offset:256
	global_load_dwordx4 v[48:51], v184, s[50:51] offset:256
	global_load_dwordx4 v[52:55], v185, s[50:51] offset:256
	global_load_dwordx4 v[56:59], v186, s[50:51] offset:256
	global_load_dwordx4 v[60:63], v187, s[50:51] offset:256
	s_nop 15
	v_add_u32_e32 v160, s58, v153
	ds_write_b128 v160, v[128:131]
	ds_write_b128 v160, v[132:135] offset:1024
	ds_write_b128 v160, v[136:139] offset:2048
	ds_write_b128 v160, v[140:143] offset:3072
	s_waitcnt lgkmcnt(0)
	s_barrier
	v_add_u32_e32 v161, s58, v156
	ds_read_b64 v[162:163], v161
	ds_read_b64 v[164:165], v161 offset:4096
	ds_read_b64 v[166:167], v161 offset:8192
	ds_read_b64 v[168:169], v161 offset:12288
	ds_read_b64 v[170:171], v161 offset:16384
	ds_read_b64 v[172:173], v161 offset:20480
	ds_read_b64 v[174:175], v161 offset:24576
	ds_read_b64 v[176:177], v161 offset:28672
	s_xor_b32 s58, s58, 0x8000
	s_waitcnt lgkmcnt(0)
	v_add_f32_e32 v162, v162, v164
	v_add_f32_e32 v163, v163, v165
	v_add_f32_e32 v162, v162, v166
	v_add_f32_e32 v163, v163, v167
	v_add_f32_e32 v162, v162, v168
	v_add_f32_e32 v163, v163, v169
	v_add_f32_e32 v162, v162, v170
	v_add_f32_e32 v163, v163, v171
	v_add_f32_e32 v162, v162, v172
	v_add_f32_e32 v163, v163, v173
	v_add_f32_e32 v162, v162, v174
	v_add_f32_e32 v163, v163, v175
	v_add_f32_e32 v162, v162, v176
	v_add_f32_e32 v163, v163, v177
	s_lshr_b32 s56, s46, 3
	s_and_b32 s56, s56, 12
	s_cmp_eq_u32 s56, 12
	s_cbranch_scc0 .Lsl_nogate_m1
	v_mul_f32_e32 v164, 0xbfb8aa3b, v162
	v_mul_f32_e32 v165, 0xbfb8aa3b, v163
	v_exp_f32_e32 v164, v164
	v_exp_f32_e32 v165, v165
	s_nop 0
	v_add_f32_e32 v164, 1.0, v164
	v_add_f32_e32 v165, 1.0, v165
	v_rcp_f32_e32 v164, v164
	v_rcp_f32_e32 v165, v165
	s_nop 0
	v_mul_f32_e32 v162, v162, v164
	v_mul_f32_e32 v163, v163, v165
.Lsl_nogate_m1:
	v_cvt_pk_bf16_f32 v162, v162, v163
	v_add_u32_e32 v164, 0x4000, v150
	v_lshlrev_b32_e32 v164, 14, v164
	s_lshl_b32 s56, s46, 6
	v_lshl_add_u32 v165, v158, 1, s56
	v_add_u32_e32 v164, v164, v165
	global_store_dword v164, v162, s[54:55]
	s_mov_b32 s46, s48
	s_waitcnt vmcnt(8)
	ds_write_b128 v188, v[0:3]
	ds_write_b128 v188, v[4:7] offset:1088
	ds_write_b128 v188, v[8:11] offset:2176
	ds_write_b128 v188, v[12:15] offset:3264
	ds_write_b128 v188, v[16:19] offset:4352
	ds_write_b128 v188, v[20:23] offset:5440
	ds_write_b128 v188, v[24:27] offset:6528
	ds_write_b128 v188, v[28:31] offset:7616
	s_waitcnt lgkmcnt(4)
	ds_read_b128 v[192:195], v189
	ds_read_b128 v[196:199], v189 offset:16
	ds_read_b128 v[200:203], v189 offset:32
	ds_read_b128 v[204:207], v189 offset:48
	ds_read_b128 v[208:211], v189 offset:128
	ds_read_b128 v[212:215], v189 offset:144
	ds_read_b128 v[216:219], v189 offset:160
	ds_read_b128 v[220:223], v189 offset:176
	s_waitcnt lgkmcnt(7)
	v_mfma_f32_32x32x16_bf16 v[128:143], v[192:195], v[64:67], 0
	s_waitcnt lgkmcnt(6)
	v_mfma_f32_32x32x16_bf16 v[128:143], v[196:199], v[68:71], v[128:143]
	s_waitcnt lgkmcnt(5)
	v_mfma_f32_32x32x16_bf16 v[128:143], v[200:203], v[72:75], v[128:143]
	s_waitcnt lgkmcnt(4)
	v_mfma_f32_32x32x16_bf16 v[128:143], v[204:207], v[76:79], v[128:143]
	s_waitcnt lgkmcnt(3)
	v_mfma_f32_32x32x16_bf16 v[128:143], v[208:211], v[80:83], v[128:143]
	s_waitcnt lgkmcnt(2)
	v_mfma_f32_32x32x16_bf16 v[128:143], v[212:215], v[84:87], v[128:143]
	s_waitcnt lgkmcnt(1)
	v_mfma_f32_32x32x16_bf16 v[128:143], v[216:219], v[88:91], v[128:143]
	s_waitcnt lgkmcnt(0)
	v_mfma_f32_32x32x16_bf16 v[128:143], v[220:223], v[92:95], v[128:143]
	s_waitcnt vmcnt(1)
	ds_write_b128 v188, v[32:35]
	ds_write_b128 v188, v[36:39] offset:1088
	ds_write_b128 v188, v[40:43] offset:2176
	ds_write_b128 v188, v[44:47] offset:3264
	ds_write_b128 v188, v[48:51] offset:4352
	ds_write_b128 v188, v[52:55] offset:5440
	ds_write_b128 v188, v[56:59] offset:6528
	ds_write_b128 v188, v[60:63] offset:7616
	s_waitcnt lgkmcnt(4)
	ds_read_b128 v[192:195], v189
	ds_read_b128 v[196:199], v189 offset:16
	ds_read_b128 v[200:203], v189 offset:32
	ds_read_b128 v[204:207], v189 offset:48
	ds_read_b128 v[208:211], v189 offset:128
	ds_read_b128 v[212:215], v189 offset:144
	ds_read_b128 v[216:219], v189 offset:160
	ds_read_b128 v[220:223], v189 offset:176
	s_waitcnt lgkmcnt(7)
	v_mfma_f32_32x32x16_bf16 v[128:143], v[192:195], v[96:99], v[128:143]
	s_waitcnt lgkmcnt(6)
	v_mfma_f32_32x32x16_bf16 v[128:143], v[196:199], v[100:103], v[128:143]
	s_waitcnt lgkmcnt(5)
	v_mfma_f32_32x32x16_bf16 v[128:143], v[200:203], v[104:107], v[128:143]
	s_waitcnt lgkmcnt(4)
	v_mfma_f32_32x32x16_bf16 v[128:143], v[204:207], v[108:111], v[128:143]
	s_waitcnt lgkmcnt(3)
	v_mfma_f32_32x32x16_bf16 v[128:143], v[208:211], v[112:115], v[128:143]
	s_waitcnt lgkmcnt(2)
	v_mfma_f32_32x32x16_bf16 v[128:143], v[212:215], v[116:119], v[128:143]
	s_waitcnt lgkmcnt(1)
	v_mfma_f32_32x32x16_bf16 v[128:143], v[216:219], v[120:123], v[128:143]
	s_waitcnt lgkmcnt(0)
	v_mfma_f32_32x32x16_bf16 v[128:143], v[220:223], v[124:127], v[128:143]
	s_add_i32 s48, s46, s60
	s_cmp_lt_u32 s57, s61
	s_cbranch_scc0 .Lsl_no3_m
	s_lshl_b32 s56, s48, 17
	v_add_u32_e32 v180, s56, v191
	v_add_u32_e32 v181, 0x4000, v180
	v_add_u32_e32 v182, 0x8000, v180
	v_add_u32_e32 v183, 0xc000, v180
	v_add_u32_e32 v184, 0x10000, v180
	v_add_u32_e32 v185, 0x14000, v180
	v_add_u32_e32 v186, 0x18000, v180
	v_add_u32_e32 v187, 0x1c000, v180
	global_load_dwordx4 v[0:3], v180, s[50:51]
	global_load_dwordx4 v[4:7], v181, s[50:51]
	global_load_dwordx4 v[8:11], v182, s[50:51]
	global_load_dwordx4 v[12:15], v183, s[50:51]
	global_load_dwordx4 v[16:19], v184, s[50:51]
	global_load_dwordx4 v[20:23], v185, s[50:51]
	global_load_dwordx4 v[24:27], v186, s[50:51]
	global_load_dwordx4 v[28:31], v187, s[50:51]
	global_load_dwordx4 v[32:35], v180, s[50:51] offset:256
	global_load_dwordx4 v[36:39], v181, s[50:51] offset:256
	global_load_dwordx4 v[40:43], v182, s[50:51] offset:256
	global_load_dwordx4 v[44:47], v183, s[50:51] offset:256
	global_load_dwordx4 v[48:51], v184, s[50:51] offset:256
	global_load_dwordx4 v[52:55], v185, s[50:51] offset:256
	global_load_dwordx4 v[56:59], v186, s[50:51] offset:256
	global_load_dwordx4 v[60:63], v187, s[50:51] offset:256

.Lsl_nogate_m2:
	v_cvt_pk_bf16_f32 v162, v162, v163
	v_add_u32_e32 v164, 0x4000, v150
	v_lshlrev_b32_e32 v164, 14, v164
	s_lshl_b32 s56, s46, 6
	v_lshl_add_u32 v165, v158, 1, s56
	v_add_u32_e32 v164, v164, v165
	global_store_dword v164, v162, s[54:55]
	s_mov_b32 s46, s48
	s_cmp_lt_u32 s57, s61
	s_cbranch_scc0 .Lsl_done
	s_waitcnt vmcnt(8)
	ds_write_b128 v188, v[0:3]
	ds_write_b128 v188, v[4:7] offset:1088
	ds_write_b128 v188, v[8:11] offset:2176
	ds_write_b128 v188, v[12:15] offset:3264
	ds_write_b128 v188, v[16:19] offset:4352
	ds_write_b128 v188, v[20:23] offset:5440
	ds_write_b128 v188, v[24:27] offset:6528
	ds_write_b128 v188, v[28:31] offset:7616
	s_waitcnt lgkmcnt(4)
	ds_read_b128 v[192:195], v189
	ds_read_b128 v[196:199], v189 offset:16
	ds_read_b128 v[200:203], v189 offset:32
	ds_read_b128 v[204:207], v189 offset:48
	ds_read_b128 v[208:211], v189 offset:128
	ds_read_b128 v[212:215], v189 offset:144
	ds_read_b128 v[216:219], v189 offset:160
	ds_read_b128 v[220:223], v189 offset:176
	s_waitcnt lgkmcnt(7)
	v_mfma_f32_32x32x16_bf16 v[128:143], v[192:195], v[64:67], 0
	s_waitcnt lgkmcnt(6)
	v_mfma_f32_32x32x16_bf16 v[128:143], v[196:199], v[68:71], v[128:143]
	s_waitcnt lgkmcnt(5)
	v_mfma_f32_32x32x16_bf16 v[128:143], v[200:203], v[72:75], v[128:143]
	s_waitcnt lgkmcnt(4)
	v_mfma_f32_32x32x16_bf16 v[128:143], v[204:207], v[76:79], v[128:143]
	s_waitcnt lgkmcnt(3)
	v_mfma_f32_32x32x16_bf16 v[128:143], v[208:211], v[80:83], v[128:143]
	s_waitcnt lgkmcnt(2)
	v_mfma_f32_32x32x16_bf16 v[128:143], v[212:215], v[84:87], v[128:143]
	s_waitcnt lgkmcnt(1)
	v_mfma_f32_32x32x16_bf16 v[128:143], v[216:219], v[88:91], v[128:143]
	s_waitcnt lgkmcnt(0)
	v_mfma_f32_32x32x16_bf16 v[128:143], v[220:223], v[92:95], v[128:143]
	s_waitcnt vmcnt(1)
	ds_write_b128 v188, v[32:35]
	ds_write_b128 v188, v[36:39] offset:1088
	ds_write_b128 v188, v[40:43] offset:2176
	ds_write_b128 v188, v[44:47] offset:3264
	ds_write_b128 v188, v[48:51] offset:4352
	ds_write_b128 v188, v[52:55] offset:5440
	ds_write_b128 v188, v[56:59] offset:6528
	ds_write_b128 v188, v[60:63] offset:7616
	s_waitcnt lgkmcnt(4)
	ds_read_b128 v[192:195], v189
	ds_read_b128 v[196:199], v189 offset:16
	ds_read_b128 v[200:203], v189 offset:32
	ds_read_b128 v[204:207], v189 offset:48
	ds_read_b128 v[208:211], v189 offset:128
	ds_read_b128 v[212:215], v189 offset:144
	ds_read_b128 v[216:219], v189 offset:160
	ds_read_b128 v[220:223], v189 offset:176
	s_waitcnt lgkmcnt(7)
	v_mfma_f32_32x32x16_bf16 v[128:143], v[192:195], v[96:99], v[128:143]
	s_waitcnt lgkmcnt(6)
	v_mfma_f32_32x32x16_bf16 v[128:143], v[196:199], v[100:103], v[128:143]
	s_waitcnt lgkmcnt(5)
	v_mfma_f32_32x32x16_bf16 v[128:143], v[200:203], v[104:107], v[128:143]
	s_waitcnt lgkmcnt(4)
	v_mfma_f32_32x32x16_bf16 v[128:143], v[204:207], v[108:111], v[128:143]
	s_waitcnt lgkmcnt(3)
	v_mfma_f32_32x32x16_bf16 v[128:143], v[208:211], v[112:115], v[128:143]
	s_waitcnt lgkmcnt(2)
	v_mfma_f32_32x32x16_bf16 v[128:143], v[212:215], v[116:119], v[128:143]
	s_waitcnt lgkmcnt(1)
	v_mfma_f32_32x32x16_bf16 v[128:143], v[216:219], v[120:123], v[128:143]
	s_waitcnt lgkmcnt(0)
	v_mfma_f32_32x32x16_bf16 v[128:143], v[220:223], v[124:127], v[128:143]
	s_nop 15
	v_add_u32_e32 v160, s58, v153
	ds_write_b128 v160, v[128:131]
	ds_write_b128 v160, v[132:135] offset:1024
	ds_write_b128 v160, v[136:139] offset:2048
	ds_write_b128 v160, v[140:143] offset:3072
	s_waitcnt lgkmcnt(0)
	s_barrier
	v_add_u32_e32 v161, s58, v156
	ds_read_b64 v[162:163], v161
	ds_read_b64 v[164:165], v161 offset:4096
	ds_read_b64 v[166:167], v161 offset:8192
	ds_read_b64 v[168:169], v161 offset:12288
	ds_read_b64 v[170:171], v161 offset:16384
	ds_read_b64 v[172:173], v161 offset:20480
	ds_read_b64 v[174:175], v161 offset:24576
	ds_read_b64 v[176:177], v161 offset:28672
	s_xor_b32 s58, s58, 0x8000
	s_waitcnt lgkmcnt(0)
	v_add_f32_e32 v162, v162, v164
	v_add_f32_e32 v163, v163, v165
	v_add_f32_e32 v162, v162, v166
	v_add_f32_e32 v163, v163, v167
	v_add_f32_e32 v162, v162, v168
	v_add_f32_e32 v163, v163, v169
	v_add_f32_e32 v162, v162, v170
	v_add_f32_e32 v163, v163, v171
	v_add_f32_e32 v162, v162, v172
	v_add_f32_e32 v163, v163, v173
	v_add_f32_e32 v162, v162, v174
	v_add_f32_e32 v163, v163, v175
	v_add_f32_e32 v162, v162, v176
	v_add_f32_e32 v163, v163, v177
	s_lshr_b32 s56, s46, 3
	s_and_b32 s56, s56, 12
	s_cmp_eq_u32 s56, 12
	s_cbranch_scc0 .Lsl_nogate_m3
	v_mul_f32_e32 v164, 0xbfb8aa3b, v162
	v_mul_f32_e32 v165, 0xbfb8aa3b, v163
	v_exp_f32_e32 v164, v164
	v_exp_f32_e32 v165, v165
	s_nop 0
	v_add_f32_e32 v164, 1.0, v164
	v_add_f32_e32 v165, 1.0, v165
	v_rcp_f32_e32 v164, v164
	v_rcp_f32_e32 v165, v165
	s_nop 0
	v_mul_f32_e32 v162, v162, v164
	v_mul_f32_e32 v163, v163, v165
.Lsl_nogate_m3:
	v_cvt_pk_bf16_f32 v162, v162, v163
	v_add_u32_e32 v164, 0x4000, v150
	v_lshlrev_b32_e32 v164, 14, v164
	s_lshl_b32 s56, s46, 6
	v_lshl_add_u32 v165, v158, 1, s56
	v_add_u32_e32 v164, v164, v165
	global_store_dword v164, v162, s[54:55]
	s_branch .Lsl_done
